# lever 2 (epilogue de-serialisation): GEMM2 epilogue requests all 16 gate loads at once instead of two waited groups of 8
# speedup vs baseline: 1.0078x; 1.0078x over previous
.LBB0_743:
	v_readlane_b32 s72, v236, 22
	v_readlane_b32 s80, v236, 30
	v_readlane_b32 s81, v236, 31
	v_readlane_b32 s82, v236, 32
	v_readlane_b32 s83, v236, 33
	v_readlane_b32 s84, v236, 34
	v_readlane_b32 s85, v236, 35
	s_cmp_lg_u32 s7, 0
	v_readlane_b32 s86, v236, 36
	v_readlane_b32 s87, v236, 37
	s_mov_b64 s[80:81], s[84:85]
	v_readlane_b32 s36, v236, 0
	s_cselect_b64 s[34:35], -1, 0
	s_cmp_eq_u32 s7, 0
	s_mov_b64 s[82:83], s[86:87]
	v_readlane_b32 s37, v236, 1
	s_cselect_b32 s37, s83, s37
	s_cselect_b32 s36, s82, s36
	s_lshl_b32 s7, s6, 4
	s_lshl_b32 s23, s30, 1
	v_lshl_add_u64 v[128:129], s[36:37], 0, v[176:177]
	s_add_i32 s36, s7, s23
	s_ashr_i32 s37, s36, 31
	s_lshl_b64 s[38:39], s[36:37], 16
	s_or_b32 s36, s36, 1
	s_ashr_i32 s37, s36, 31
	v_lshl_add_u64 v[190:191], v[128:129], 0, s[38:39]
	s_lshl_b64 s[36:37], s[36:37], 16
	v_lshl_add_u64 v[192:193], v[128:129], 0, s[36:37]
	v_add_co_u32_e32 v128, vcc, s44, v190
	global_load_dwordx4 v[156:159], v[190:191], off
	global_load_dwordx4 v[152:155], v[192:193], off
	v_addc_co_u32_e32 v129, vcc, 0, v191, vcc
	v_add_co_u32_e32 v130, vcc, s44, v192
	v_lshl_add_u32 v188, s6, 8, v204
	s_nop 0
	v_addc_co_u32_e32 v131, vcc, 0, v193, vcc
	global_load_dwordx4 v[148:151], v[128:129], off
	global_load_dwordx4 v[144:147], v[130:131], off
	v_add_co_u32_e32 v128, vcc, s45, v190
	v_ashrrev_i32_e32 v189, 31, v188
	s_nop 0
	v_addc_co_u32_e32 v129, vcc, 0, v191, vcc
	v_add_co_u32_e32 v130, vcc, s45, v192
	v_lshlrev_b64 v[160:161], 12, v[188:189]
	s_nop 0
	v_addc_co_u32_e32 v131, vcc, 0, v193, vcc
	global_load_dwordx4 v[140:143], v[128:129], off
	global_load_dwordx4 v[136:139], v[130:131], off
	v_add_co_u32_e32 v128, vcc, s46, v190
	v_readlane_b32 s74, v236, 24
	s_nop 0
	v_addc_co_u32_e32 v129, vcc, 0, v191, vcc
	v_add_co_u32_e32 v130, vcc, s46, v192
	v_readlane_b32 s75, v236, 25
	s_nop 0
	v_addc_co_u32_e32 v131, vcc, 0, v193, vcc
	global_load_dwordx4 v[132:135], v[128:129], off
	s_nop 0
	global_load_dwordx4 v[128:131], v[130:131], off
	v_add_co_u32_e32 v248, vcc, 0x8000, v190
	s_nop 1
	v_addc_co_u32_e32 v249, vcc, 0, v191, vcc
	global_load_dwordx4 v[210:213], v[248:249], off
	v_add_co_u32_e32 v250, vcc, 0x8000, v192
	s_nop 1
	v_addc_co_u32_e32 v251, vcc, 0, v193, vcc
	global_load_dwordx4 v[214:217], v[250:251], off
	v_add_co_u32_e32 v248, vcc, 0xa000, v190
	s_nop 1
	v_addc_co_u32_e32 v249, vcc, 0, v191, vcc
	global_load_dwordx4 v[218:221], v[248:249], off
	v_add_co_u32_e32 v250, vcc, 0xa000, v192
	s_nop 1
	v_addc_co_u32_e32 v251, vcc, 0, v193, vcc
	global_load_dwordx4 v[222:225], v[250:251], off
	v_add_co_u32_e32 v248, vcc, 0xc000, v190
	s_nop 1
	v_addc_co_u32_e32 v249, vcc, 0, v191, vcc
	global_load_dwordx4 v[226:229], v[248:249], off
	v_add_co_u32_e32 v250, vcc, 0xc000, v192
	s_nop 1
	v_addc_co_u32_e32 v251, vcc, 0, v193, vcc
	global_load_dwordx4 v[230:233], v[250:251], off
	v_add_co_u32_e32 v248, vcc, 0xe000, v190
	s_nop 1
	v_addc_co_u32_e32 v249, vcc, 0, v191, vcc
	global_load_dwordx4 v[240:243], v[248:249], off
	v_add_co_u32_e32 v250, vcc, 0xe000, v192
	s_nop 1
	v_addc_co_u32_e32 v251, vcc, 0, v193, vcc
	global_load_dwordx4 v[244:247], v[250:251], off
	v_readlane_b32 s78, v236, 28
	v_readlane_b32 s79, v236, 29
	v_lshl_or_b32 v186, s30, 8, v206
	v_lshl_add_u64 v[194:195], s[52:53], 0, v[160:161]
	s_mov_b64 s[74:75], s[78:79]
	v_ashrrev_i32_e32 v187, 31, v186
	s_and_b64 vcc, exec, s[34:35]
	v_readlane_b32 s73, v236, 23
	v_readlane_b32 s76, v236, 26
	v_readlane_b32 s77, v236, 27
	s_waitcnt vmcnt(8)
	v_lshlrev_b32_e32 v160, 16, v156
	v_and_b32_e32 v161, 0xffff0000, v156
	v_lshlrev_b32_e32 v162, 16, v158
	v_and_b32_e32 v163, 0xffff0000, v158
	v_lshlrev_b32_e32 v208, 16, v157
	v_and_b32_e32 v209, 0xffff0000, v157
	v_lshlrev_b32_e32 v158, 16, v159
	v_and_b32_e32 v159, 0xffff0000, v159
	v_pk_mul_f32 v[160:161], v[124:125], v[160:161]
	v_pk_mul_f32 v[156:157], v[120:121], v[162:163]
	v_pk_mul_f32 v[162:163], v[126:127], v[208:209]
	v_pk_mul_f32 v[158:159], v[122:123], v[158:159]
	s_cbranch_vccz .LBB0_745
	v_cvt_pk_bf16_f32 v160, v160, v161
	v_cvt_pk_bf16_f32 v161, v162, v163
	v_cvt_pk_bf16_f32 v162, v156, v157
	v_cvt_pk_bf16_f32 v163, v158, v159
	v_lshl_add_u64 v[156:157], v[186:187], 1, v[194:195]
	global_store_dwordx4 v[156:157], v[160:163], off
	s_branch .LBB0_746

.LBB0_767:
	s_andn2_b64 vcc, exec, s[30:31]
	v_add_co_u32_e32 v128, vcc, 0x8000, v190
	v_lshlrev_b64 v[160:161], 12, v[188:189]
	s_nop 0
	v_addc_co_u32_e32 v129, vcc, 0, v191, vcc
	v_add_co_u32_e32 v130, vcc, 0x8000, v192
	s_nop 1
	v_addc_co_u32_e32 v131, vcc, 0, v193, vcc
	s_and_b64 vcc, exec, s[34:35]
	s_cbranch_vccz .Lg2e_h0
	s_waitcnt vmcnt(8)
	s_branch .Lg2e_j

.Lg2e_j:
	v_mov_b64_e32 v[156:157], v[210:211]
	v_mov_b64_e32 v[158:159], v[212:213]
	v_mov_b64_e32 v[152:153], v[214:215]
	v_mov_b64_e32 v[154:155], v[216:217]
	v_add_co_u32_e32 v128, vcc, 0xa000, v190
	s_nop 0
	v_lshlrev_b32_e32 v162, 16, v158
	v_addc_co_u32_e32 v129, vcc, 0, v191, vcc
	v_add_co_u32_e32 v130, vcc, 0xa000, v192
	v_and_b32_e32 v163, 0xffff0000, v158
	s_nop 0
	v_addc_co_u32_e32 v131, vcc, 0, v193, vcc
	v_mov_b64_e32 v[148:149], v[218:219]
	v_mov_b64_e32 v[150:151], v[220:221]
	v_mov_b64_e32 v[144:145], v[222:223]
	v_mov_b64_e32 v[146:147], v[224:225]
	v_add_co_u32_e32 v128, vcc, 0xc000, v190
	v_lshlrev_b32_e32 v158, 16, v159
	s_nop 0
	v_addc_co_u32_e32 v129, vcc, 0, v191, vcc
	v_add_co_u32_e32 v130, vcc, 0xc000, v192
	v_and_b32_e32 v159, 0xffff0000, v159
	s_nop 0
	v_addc_co_u32_e32 v131, vcc, 0, v193, vcc
	v_mov_b64_e32 v[140:141], v[226:227]
	v_mov_b64_e32 v[142:143], v[228:229]
	v_mov_b64_e32 v[136:137], v[230:231]
	v_mov_b64_e32 v[138:139], v[232:233]
	v_add_co_u32_e32 v128, vcc, 0xe000, v190
	v_pk_mul_f32 v[158:159], v[58:59], v[158:159]
	s_nop 0
	v_addc_co_u32_e32 v129, vcc, 0, v191, vcc
	v_add_co_u32_e32 v130, vcc, 0xe000, v192
	v_lshl_add_u64 v[190:191], v[160:161], 0, s[8:9]
	s_nop 0
	v_addc_co_u32_e32 v131, vcc, 0, v193, vcc
	v_mov_b64_e32 v[132:133], v[240:241]
	v_mov_b64_e32 v[134:135], v[242:243]
	s_nop 0
	v_mov_b64_e32 v[128:129], v[244:245]
	v_mov_b64_e32 v[130:131], v[246:247]
	v_lshlrev_b32_e32 v160, 16, v156
	v_and_b32_e32 v161, 0xffff0000, v156
	v_lshlrev_b32_e32 v192, 16, v157
	v_and_b32_e32 v193, 0xffff0000, v157
	v_pk_mul_f32 v[160:161], v[60:61], v[160:161]
	v_pk_mul_f32 v[156:157], v[56:57], v[162:163]
	v_pk_mul_f32 v[162:163], v[62:63], v[192:193]
	s_and_b64 vcc, exec, s[6:7]
	v_lshl_add_u64 v[190:191], s[52:53], 0, v[190:191]
	s_cbranch_vccnz .LBB0_769
	v_cvt_pk_bf16_f32 v160, v160, v161
	v_cvt_pk_bf16_f32 v161, v162, v163
	v_cvt_pk_bf16_f32 v162, v156, v157
	v_cvt_pk_bf16_f32 v163, v158, v159
	v_lshl_add_u64 v[156:157], v[186:187], 1, v[190:191]
	s_mov_b64 s[30:31], 0
	global_store_dwordx4 v[156:157], v[160:163], off
	s_branch .LBB0_770

.LBB0_770:
	s_nop 0
	v_lshlrev_b32_e32 v156, 16, v152
	v_and_b32_e32 v157, 0xffff0000, v152
	v_lshlrev_b32_e32 v152, 16, v153
	v_and_b32_e32 v153, 0xffff0000, v153
	s_andn2_b64 vcc, exec, s[30:31]
	v_lshlrev_b32_e32 v158, 16, v154
	v_and_b32_e32 v159, 0xffff0000, v154
	v_pk_mul_f32 v[162:163], v[30:31], v[152:153]
	v_lshlrev_b32_e32 v152, 16, v155
	v_and_b32_e32 v153, 0xffff0000, v155
	v_pk_mul_f32 v[160:161], v[28:29], v[156:157]
	v_pk_mul_f32 v[156:157], v[24:25], v[158:159]
	s_and_b64 vcc, exec, s[6:7]
	v_pk_mul_f32 v[158:159], v[26:27], v[152:153]
	s_cbranch_vccnz .LBB0_772
	v_cvt_pk_bf16_f32 v152, v160, v161
	v_cvt_pk_bf16_f32 v153, v162, v163
	v_cvt_pk_bf16_f32 v154, v156, v157
	v_cvt_pk_bf16_f32 v155, v158, v159
	v_lshl_add_u64 v[156:157], v[186:187], 1, v[190:191]
	s_mov_b64 s[30:31], 0
	global_store_dwordx4 v[156:157], v[152:155], off offset:256
	s_branch .LBB0_773

.LBB0_773:
	s_nop 0
	v_lshlrev_b64 v[152:153], 12, v[188:189]
	v_lshl_add_u64 v[160:161], v[152:153], 0, s[16:17]
	s_nop 0
	v_lshlrev_b32_e32 v152, 16, v148
	v_and_b32_e32 v153, 0xffff0000, v148
	v_lshlrev_b32_e32 v148, 16, v149
	v_and_b32_e32 v149, 0xffff0000, v149
	s_andn2_b64 vcc, exec, s[30:31]
	v_lshlrev_b32_e32 v154, 16, v150
	v_and_b32_e32 v155, 0xffff0000, v150
	v_pk_mul_f32 v[158:159], v[54:55], v[148:149]
	v_lshlrev_b32_e32 v148, 16, v151
	v_and_b32_e32 v149, 0xffff0000, v151
	v_pk_mul_f32 v[156:157], v[52:53], v[152:153]
	v_pk_mul_f32 v[152:153], v[48:49], v[154:155]
	v_pk_mul_f32 v[154:155], v[50:51], v[148:149]
	s_and_b64 vcc, exec, s[6:7]
	v_lshl_add_u64 v[160:161], s[52:53], 0, v[160:161]
	s_cbranch_vccnz .LBB0_775
	v_cvt_pk_bf16_f32 v148, v156, v157
	v_cvt_pk_bf16_f32 v149, v158, v159
	v_cvt_pk_bf16_f32 v150, v152, v153
	v_cvt_pk_bf16_f32 v151, v154, v155
	v_lshl_add_u64 v[152:153], v[186:187], 1, v[160:161]
	s_mov_b64 s[30:31], 0
	global_store_dwordx4 v[152:153], v[148:151], off
	s_branch .LBB0_776

.LBB0_776:
	s_nop 0
	v_lshlrev_b32_e32 v148, 16, v144
	v_and_b32_e32 v149, 0xffff0000, v144
	v_lshlrev_b32_e32 v144, 16, v145
	v_and_b32_e32 v145, 0xffff0000, v145
	s_andn2_b64 vcc, exec, s[30:31]
	v_lshlrev_b32_e32 v150, 16, v146
	v_and_b32_e32 v151, 0xffff0000, v146
	v_pk_mul_f32 v[154:155], v[22:23], v[144:145]
	v_lshlrev_b32_e32 v144, 16, v147
	v_and_b32_e32 v145, 0xffff0000, v147
	v_pk_mul_f32 v[152:153], v[20:21], v[148:149]
	v_pk_mul_f32 v[148:149], v[16:17], v[150:151]
	s_and_b64 vcc, exec, s[6:7]
	v_pk_mul_f32 v[150:151], v[18:19], v[144:145]
	s_cbranch_vccnz .LBB0_778
	v_cvt_pk_bf16_f32 v144, v152, v153
	v_cvt_pk_bf16_f32 v145, v154, v155
	v_cvt_pk_bf16_f32 v146, v148, v149
	v_cvt_pk_bf16_f32 v147, v150, v151
	v_lshl_add_u64 v[148:149], v[186:187], 1, v[160:161]
	s_mov_b64 s[30:31], 0
	global_store_dwordx4 v[148:149], v[144:147], off offset:256
	s_branch .LBB0_779

.LBB0_779:
	s_nop 0
	v_lshlrev_b64 v[144:145], 12, v[188:189]
	v_lshl_add_u64 v[152:153], v[144:145], 0, s[18:19]
	s_nop 0
	v_lshlrev_b32_e32 v144, 16, v140
	v_and_b32_e32 v145, 0xffff0000, v140
	v_lshlrev_b32_e32 v140, 16, v141
	v_and_b32_e32 v141, 0xffff0000, v141
	s_andn2_b64 vcc, exec, s[30:31]
	v_lshlrev_b32_e32 v146, 16, v142
	v_and_b32_e32 v147, 0xffff0000, v142
	v_pk_mul_f32 v[150:151], v[46:47], v[140:141]
	v_lshlrev_b32_e32 v140, 16, v143
	v_and_b32_e32 v141, 0xffff0000, v143
	v_pk_mul_f32 v[148:149], v[44:45], v[144:145]
	v_pk_mul_f32 v[144:145], v[40:41], v[146:147]
	v_pk_mul_f32 v[146:147], v[42:43], v[140:141]
	s_and_b64 vcc, exec, s[6:7]
	v_lshl_add_u64 v[152:153], s[52:53], 0, v[152:153]
	s_cbranch_vccnz .LBB0_781
	v_cvt_pk_bf16_f32 v140, v148, v149
	v_cvt_pk_bf16_f32 v141, v150, v151
	v_cvt_pk_bf16_f32 v142, v144, v145
	v_cvt_pk_bf16_f32 v143, v146, v147
	v_lshl_add_u64 v[144:145], v[186:187], 1, v[152:153]
	s_mov_b64 s[30:31], 0
	global_store_dwordx4 v[144:145], v[140:143], off
	s_branch .LBB0_782

.LBB0_782:
	s_nop 0
	v_lshlrev_b32_e32 v140, 16, v136
	v_and_b32_e32 v141, 0xffff0000, v136
	v_lshlrev_b32_e32 v136, 16, v137
	v_and_b32_e32 v137, 0xffff0000, v137
	s_andn2_b64 vcc, exec, s[30:31]
	v_lshlrev_b32_e32 v142, 16, v138
	v_and_b32_e32 v143, 0xffff0000, v138
	v_pk_mul_f32 v[146:147], v[14:15], v[136:137]
	v_lshlrev_b32_e32 v136, 16, v139
	v_and_b32_e32 v137, 0xffff0000, v139
	v_pk_mul_f32 v[144:145], v[12:13], v[140:141]
	v_pk_mul_f32 v[140:141], v[8:9], v[142:143]
	s_and_b64 vcc, exec, s[6:7]
	v_pk_mul_f32 v[142:143], v[10:11], v[136:137]
	s_cbranch_vccnz .LBB0_784
	v_cvt_pk_bf16_f32 v136, v144, v145
	v_cvt_pk_bf16_f32 v137, v146, v147
	v_cvt_pk_bf16_f32 v138, v140, v141
	v_cvt_pk_bf16_f32 v139, v142, v143
	v_lshl_add_u64 v[140:141], v[186:187], 1, v[152:153]
	s_mov_b64 s[30:31], 0
	global_store_dwordx4 v[140:141], v[136:139], off offset:256
	s_branch .LBB0_785

.LBB0_785:
	s_nop 0
	v_lshlrev_b64 v[136:137], 12, v[188:189]
	v_lshl_add_u64 v[144:145], v[136:137], 0, s[20:21]
	s_nop 0
	v_lshlrev_b32_e32 v136, 16, v132
	v_and_b32_e32 v137, 0xffff0000, v132
	v_lshlrev_b32_e32 v132, 16, v133
	v_and_b32_e32 v133, 0xffff0000, v133
	s_andn2_b64 vcc, exec, s[30:31]
	v_lshlrev_b32_e32 v138, 16, v134
	v_and_b32_e32 v139, 0xffff0000, v134
	v_pk_mul_f32 v[142:143], v[38:39], v[132:133]
	v_lshlrev_b32_e32 v132, 16, v135
	v_and_b32_e32 v133, 0xffff0000, v135
	v_pk_mul_f32 v[140:141], v[36:37], v[136:137]
	v_pk_mul_f32 v[136:137], v[32:33], v[138:139]
	v_pk_mul_f32 v[138:139], v[34:35], v[132:133]
	s_and_b64 vcc, exec, s[6:7]
	v_lshl_add_u64 v[144:145], s[52:53], 0, v[144:145]
	s_cbranch_vccnz .LBB0_787
	v_cvt_pk_bf16_f32 v132, v140, v141
	v_cvt_pk_bf16_f32 v133, v142, v143
	v_cvt_pk_bf16_f32 v134, v136, v137
	v_cvt_pk_bf16_f32 v135, v138, v139
	v_lshl_add_u64 v[136:137], v[186:187], 1, v[144:145]
	s_mov_b64 s[30:31], 0
	global_store_dwordx4 v[136:137], v[132:135], off
	s_branch .LBB0_788

.LBB0_788:
	s_nop 0
	v_lshlrev_b32_e32 v132, 16, v128
	v_and_b32_e32 v133, 0xffff0000, v128
	v_lshlrev_b32_e32 v128, 16, v129
	v_and_b32_e32 v129, 0xffff0000, v129
	s_andn2_b64 vcc, exec, s[30:31]
	v_lshlrev_b32_e32 v134, 16, v130
	v_and_b32_e32 v135, 0xffff0000, v130
	v_pk_mul_f32 v[138:139], v[6:7], v[128:129]
	v_lshlrev_b32_e32 v128, 16, v131
	v_and_b32_e32 v129, 0xffff0000, v131
	v_pk_mul_f32 v[136:137], v[4:5], v[132:133]
	v_pk_mul_f32 v[132:133], v[0:1], v[134:135]
	s_and_b64 vcc, exec, s[6:7]
	v_pk_mul_f32 v[134:135], v[2:3], v[128:129]
	s_cbranch_vccnz .LBB0_790
	v_cvt_pk_bf16_f32 v128, v136, v137
	v_cvt_pk_bf16_f32 v129, v138, v139
	v_cvt_pk_bf16_f32 v130, v132, v133
	v_cvt_pk_bf16_f32 v131, v134, v135
	v_lshl_add_u64 v[132:133], v[186:187], 1, v[144:145]
	s_mov_b64 s[30:31], 0
	global_store_dwordx4 v[132:133], v[128:131], off offset:256
	s_andn2_b64 vcc, exec, s[30:31]
	s_andn2_b64 vcc, exec, s[4:5]
	s_mov_b64 s[4:5], -1
	s_cbranch_vccnz .LBB0_732
	s_branch .LBB0_791
